# v24 with the per-iteration s_setprio flips removed from the MLA loop (static raise for waves 4-7 kept)
# baseline (speedup 1.0000x reference)
.Lm_noload:
	s_cmp_gt_i32 s20, s35
	s_cbranch_scc1 .LBB0_379
	s_bitcmp1_b32 s20, 0
	s_cselect_b32 s38, 0xb400, 0
	v_add_u32_e32 v8, s38, v191
	ds_read_b128 v[10:13], v8
	ds_read_b128 v[14:17], v8 offset:32
	ds_read_b128 v[202:205], v8 offset:64
	ds_read_b128 v[206:209], v8 offset:96
	v_add_u32_e32 v197, s38, v196
	v_xor_b32_e32 v84, 0x80000000, v192
	v_mov_b32_e32 v85, v84
	v_mov_b32_e32 v86, v84
	v_mov_b32_e32 v87, v84
	v_mov_b32_e32 v88, v84
	v_mov_b32_e32 v89, v84
	v_mov_b32_e32 v90, v84
	v_mov_b32_e32 v91, v84
	v_mov_b32_e32 v92, v84
	v_mov_b32_e32 v93, v84
	v_mov_b32_e32 v94, v84
	v_mov_b32_e32 v95, v84
	v_mov_b32_e32 v96, v84
	v_mov_b32_e32 v97, v84
	v_mov_b32_e32 v98, v84
	v_mov_b32_e32 v99, v84
	s_waitcnt lgkmcnt(3)
	v_mfma_f32_32x32x16_bf16 v[100:115], v[10:13], v[116:119], v[84:99]
	ds_read_b128 v[10:13], v8 offset:128
	s_waitcnt lgkmcnt(3)
	v_mfma_f32_32x32x16_bf16 v[100:115], v[14:17], v[120:123], v[100:115]
	ds_read_b128 v[14:17], v8 offset:160
	s_waitcnt lgkmcnt(3)
	v_mfma_f32_32x32x16_bf16 v[100:115], v[202:205], v[124:127], v[100:115]
	ds_read_b128 v[202:205], v8 offset:192
	s_waitcnt lgkmcnt(3)
	v_mfma_f32_32x32x16_bf16 v[100:115], v[206:209], v[132:135], v[100:115]
	ds_read_b128 v[206:209], v8 offset:224
	s_waitcnt lgkmcnt(3)
	v_mfma_f32_32x32x16_bf16 v[100:115], v[10:13], v[136:139], v[100:115]
	ds_read_b128 v[10:13], v8 offset:256
	s_waitcnt lgkmcnt(3)
	v_mfma_f32_32x32x16_bf16 v[100:115], v[14:17], v[140:143], v[100:115]
	ds_read_b128 v[14:17], v8 offset:288
	s_waitcnt lgkmcnt(3)
	v_mfma_f32_32x32x16_bf16 v[100:115], v[202:205], v[144:147], v[100:115]
	ds_read_b128 v[202:205], v8 offset:320
	s_waitcnt lgkmcnt(3)
	v_mfma_f32_32x32x16_bf16 v[100:115], v[206:209], v[148:151], v[100:115]
	ds_read_b128 v[206:209], v8 offset:352
	s_waitcnt lgkmcnt(3)
	v_mfma_f32_32x32x16_bf16 v[100:115], v[10:13], v[152:155], v[100:115]
	ds_read_b128 v[10:13], v8 offset:12800
	s_waitcnt lgkmcnt(3)
	v_mfma_f32_32x32x16_bf16 v[100:115], v[14:17], v[156:159], v[100:115]
	ds_read_b128 v[14:17], v8 offset:12832
	s_waitcnt lgkmcnt(3)
	v_mfma_f32_32x32x16_bf16 v[100:115], v[202:205], v[160:163], v[100:115]
	ds_read_b128 v[202:205], v8 offset:12864
	s_waitcnt lgkmcnt(3)
	v_mfma_f32_32x32x16_bf16 v[100:115], v[206:209], v[164:167], v[100:115]
	ds_read_b128 v[206:209], v8 offset:12896
	s_waitcnt lgkmcnt(3)
	v_mfma_f32_32x32x16_bf16 v[84:99], v[10:13], v[116:119], v[84:99]
	ds_read_b128 v[10:13], v8 offset:12928
	s_waitcnt lgkmcnt(3)
	v_mfma_f32_32x32x16_bf16 v[84:99], v[14:17], v[120:123], v[84:99]
	ds_read_b128 v[14:17], v8 offset:12960
	s_waitcnt lgkmcnt(3)
	v_mfma_f32_32x32x16_bf16 v[84:99], v[202:205], v[124:127], v[84:99]
	ds_read_b128 v[202:205], v8 offset:12992
	s_waitcnt lgkmcnt(3)
	v_mfma_f32_32x32x16_bf16 v[84:99], v[206:209], v[132:135], v[84:99]
	ds_read_b128 v[206:209], v8 offset:13024
	s_waitcnt lgkmcnt(3)
	v_mfma_f32_32x32x16_bf16 v[84:99], v[10:13], v[136:139], v[84:99]
	ds_read_b128 v[10:13], v8 offset:13056
	s_waitcnt lgkmcnt(3)
	v_mfma_f32_32x32x16_bf16 v[84:99], v[14:17], v[140:143], v[84:99]
	ds_read_b128 v[14:17], v8 offset:13088
	v_max_f32_e32 v235, v101, v101
	v_max_f32_e32 v237, v100, v100
	v_max_f32_e32 v235, v237, v235
	v_max3_f32 v235, v235, v102, v103
	v_max3_f32 v235, v235, v104, v105
	v_max3_f32 v235, v235, v106, v107
	v_max3_f32 v235, v235, v108, v109
	v_max3_f32 v235, v235, v110, v111
	v_max3_f32 v235, v235, v112, v113
	v_max3_f32 v235, v235, v114, v115
	s_waitcnt lgkmcnt(3)
	v_mfma_f32_32x32x16_bf16 v[84:99], v[202:205], v[144:147], v[84:99]
	ds_read_b128 v[202:205], v8 offset:13120
	v_mov_b32_e32 v237, v235
	v_mov_b32_e32 v239, v235
	s_waitcnt lgkmcnt(3)
	v_mfma_f32_32x32x16_bf16 v[84:99], v[206:209], v[148:151], v[84:99]
	ds_read_b128 v[206:209], v8 offset:13152
	v_permlane32_swap_b32_e32 v237, v239
	v_cndmask_b32_e64 v237, v237, v239, s[4:5]
	v_max_f32_e32 v237, v237, v237
	v_max_f32_e32 v236, v235, v237
	v_cmp_lt_f32_e32 vcc, s29, v236
	s_cmp_lg_u64 vcc, 0
	s_cselect_b64 s[20:21], -1, 0
	s_cbranch_vccnz .Lm_R1
